# in-proj GEMM K-loops: LDS-DMA via scalar base + 32-bit lane offset (no per-DMA 64-bit VALU adds), +kstep via inst offset with M0 compensated
# baseline (speedup 1.0000x reference)
; #define PG8_STAGE(bufoff, gbase, voff) do { _Pragma("unroll") for (int _i = 0; _i < 2; ++_i) \
;         __builtin_amdgcn_global_load_lds((const unsigned*)((const char*)(gbase) + (voff)[_i]), (PG8_LAS unsigned*)(lds + (bufoff) + ldsw + _i * 8192), 16, 0, 0); } while (0)
; #define PG8_LDA(dst, b, h) do { _Pragma("unroll") for (int m = 0; m < 4; ++m) _Pragma("unroll") for (int k = 0; k < 2; ++k) dst[m][k] = *(const PG8_LAS bf16x8*)(lds + PG8_SA(b, h) + aoff + m * 2048 + k * 1024); } while (0)
; #define PG8_LDB(dst, b, h) do { _Pragma("unroll") for (int n = 0; n < 2; ++n) _Pragma("unroll") for (int k = 0; k < 2; ++k) dst[n][k] = *(const PG8_LAS bf16x8*)(lds + PG8_SB(b, h) + boff + n * 2048 + k * 1024); } while (0)
; #define PG8_MMA(ai, bj, At, Bt) do { __builtin_amdgcn_s_setprio(1); _Pragma("unroll") for (int m = 0; m < 4; ++m) _Pragma("unroll") for (int n = 0; n < 2; ++n) _Pragma("unroll") for (int k = 0; k < 2; ++k) \
;         acc[ai][bj][m][n] = __builtin_amdgcn_mfma_f32_16x16x32_bf16(Bt[n][k], At[m][k], acc[ai][bj][m][n], 0, 0, 0); __builtin_amdgcn_s_setprio(0); } while (0)
; #define PG8_WAIT_V(n) asm volatile("s_waitcnt vmcnt(" #n ")" ::: "memory")
; #define PG8_WAIT_L(n) asm volatile("s_waitcnt lgkmcnt(" #n ")" ::: "memory")
; #define PG8_BAR __builtin_amdgcn_s_barrier()
; #define PG8_SCHED __builtin_amdgcn_sched_barrier(0)
; template <class Epi, class Sched, bool ALIGN_EPI = false, bool SP2 = false>
; __device__ __forceinline__ void gemm_phase(PG8_LAS unsigned char* lds, const Gemm g, const Sched& S, const Epi& E) {
;     ...
;             PG8_LDB(B0, 0, 0); PG8_LDB(B1, 0, 1); PG8_SCHED; PG8_LDA(At, 0, 0); PG8_STAGE(PG8_SA(1, 1), a1 + hstep, voffA);
;             PG8_WAIT_V(8); PG8_WAIT_L(0); PG8_BAR; PG8_MMA(0, 0, At, B0); PG8_MMA(0, 1, At, B1); PG8_BAR; PG8_SCHED;
;             PG8_LDA(At, 0, 1); PG8_STAGE(PG8_SB(0, 0), b2, voffB); PG8_STAGE(PG8_SB(0, 1), b2 + hstep, voffB); PG8_STAGE(PG8_SA(0, 0), a2, voffA);
;             PG8_WAIT_V(8); PG8_WAIT_L(0); PG8_BAR; PG8_MMA(1, 0, At, B0); PG8_MMA(1, 1, At, B1); PG8_BAR; PG8_SCHED;
.LBB0_114:
	s_add_u32 s20, s8, 0xfffc0080
	s_addc_u32 s21, s9, -1
	s_add_i32 s41, 0, 0x10000
	s_cmp_eq_u32 s40, 12
	s_cselect_b32 s35, s13, s21
	s_cselect_b32 s34, s22, s20
	v_add_u32_e32 v0, s41, v154
	s_cselect_b32 s31, s11, s39
	s_cselect_b32 s30, s23, s38
	s_add_i32 s20, 0, 0x14000
	ds_read_b128 v[158:161], v0
	ds_read_b128 v[162:165], v0 offset:1024
	ds_read_b128 v[166:169], v0 offset:2048
	ds_read_b128 v[170:173], v0 offset:3072
	v_add_u32_e32 v0, s20, v154
	ds_read_b128 v[174:177], v0
	ds_read_b128 v[178:181], v0 offset:1024
	ds_read_b128 v[182:185], v0 offset:2048
	ds_read_b128 v[186:189], v0 offset:3072
	s_add_i32 m0, s46, 0xc000
	ds_read_b128 v[190:193], v156
	ds_read_b128 v[194:197], v156 offset:1024
	ds_read_b128 v[206:209], v156 offset:2048
	ds_read_b128 v[210:213], v156 offset:3072
	ds_read_b128 v[214:217], v156 offset:4096
	ds_read_b128 v[218:221], v156 offset:5120
	ds_read_b128 v[222:225], v156 offset:6144
	ds_read_b128 v[226:229], v156 offset:7168
	global_load_lds_dwordx4 v146, s[8:9]
	s_add_i32 m0, s46, 0xe000
	s_nop 0
	global_load_lds_dwordx4 v148, s[8:9]
	s_waitcnt vmcnt(8)
	s_waitcnt lgkmcnt(0)
	s_barrier
	s_setprio 1
	v_mfma_f32_16x16x32_bf16 v[126:129], v[158:161], v[190:193], v[126:129]
	v_mfma_f32_16x16x32_bf16 v[122:125], v[166:169], v[190:193], v[122:125]
	v_mfma_f32_16x16x32_bf16 v[114:117], v[158:161], v[206:209], v[114:117]
	v_mfma_f32_16x16x32_bf16 v[106:109], v[166:169], v[206:209], v[106:109]
	v_mfma_f32_16x16x32_bf16 v[98:101], v[158:161], v[214:217], v[98:101]
	v_mfma_f32_16x16x32_bf16 v[90:93], v[166:169], v[214:217], v[90:93]
	v_mfma_f32_16x16x32_bf16 v[82:85], v[158:161], v[222:225], v[82:85]
	v_mfma_f32_16x16x32_bf16 v[74:77], v[166:169], v[222:225], v[74:77]
	v_mfma_f32_16x16x32_bf16 v[126:129], v[162:165], v[194:197], v[126:129]
	v_mfma_f32_16x16x32_bf16 v[122:125], v[170:173], v[194:197], v[122:125]
	v_mfma_f32_16x16x32_bf16 v[114:117], v[162:165], v[210:213], v[114:117]
	v_mfma_f32_16x16x32_bf16 v[106:109], v[170:173], v[210:213], v[106:109]
	v_mfma_f32_16x16x32_bf16 v[98:101], v[162:165], v[218:221], v[98:101]
	v_mfma_f32_16x16x32_bf16 v[90:93], v[170:173], v[218:221], v[90:93]
	v_mfma_f32_16x16x32_bf16 v[82:85], v[162:165], v[226:229], v[82:85]
	v_mfma_f32_16x16x32_bf16 v[74:77], v[170:173], v[226:229], v[74:77]
	v_mfma_f32_16x16x32_bf16 v[118:121], v[174:177], v[190:193], v[118:121]
	v_mfma_f32_16x16x32_bf16 v[110:113], v[182:185], v[190:193], v[110:113]
	v_mfma_f32_16x16x32_bf16 v[102:105], v[174:177], v[206:209], v[102:105]
	v_mfma_f32_16x16x32_bf16 v[94:97], v[182:185], v[206:209], v[94:97]
	v_mfma_f32_16x16x32_bf16 v[86:89], v[174:177], v[214:217], v[86:89]
	v_mfma_f32_16x16x32_bf16 v[78:81], v[182:185], v[214:217], v[78:81]
	v_mfma_f32_16x16x32_bf16 v[70:73], v[174:177], v[222:225], v[70:73]
	v_mfma_f32_16x16x32_bf16 v[66:69], v[182:185], v[222:225], v[66:69]
	v_mfma_f32_16x16x32_bf16 v[118:121], v[178:181], v[194:197], v[118:121]
	v_mfma_f32_16x16x32_bf16 v[110:113], v[186:189], v[194:197], v[110:113]
	v_mfma_f32_16x16x32_bf16 v[102:105], v[178:181], v[210:213], v[102:105]
	v_mfma_f32_16x16x32_bf16 v[94:97], v[186:189], v[210:213], v[94:97]
	v_mfma_f32_16x16x32_bf16 v[86:89], v[178:181], v[218:221], v[86:89]
	v_mfma_f32_16x16x32_bf16 v[78:81], v[186:189], v[218:221], v[78:81]
	v_mfma_f32_16x16x32_bf16 v[70:73], v[178:181], v[226:229], v[70:73]
	v_mfma_f32_16x16x32_bf16 v[66:69], v[186:189], v[226:229], v[66:69]
	s_setprio 0
	s_barrier
	s_add_i32 s21, s41, s29
	s_mov_b32 m0, s21
	ds_read_b128 v[190:193], v156 offset:16384
	ds_read_b128 v[194:197], v156 offset:17408
	ds_read_b128 v[206:209], v156 offset:18432
	ds_read_b128 v[210:213], v156 offset:19456
	ds_read_b128 v[214:217], v156 offset:20480
	ds_read_b128 v[218:221], v156 offset:21504
	ds_read_b128 v[222:225], v156 offset:22528
	ds_read_b128 v[226:229], v156 offset:23552
	global_load_lds_dwordx4 v134, s[30:31]
	s_add_i32 m0, s21, 0x2000
	s_add_u32 s82, s30, 0x40000
	s_addc_u32 s83, s31, 0
	s_add_i32 s20, s20, s29
	global_load_lds_dwordx4 v130, s[30:31]
	s_mov_b32 m0, s20
	s_nop 0
	global_load_lds_dwordx4 v134, s[82:83]
	s_add_i32 m0, s20, 0x2000
	s_nop 0
	global_load_lds_dwordx4 v130, s[82:83]
	s_mov_b32 m0, s46
	s_nop 0
	global_load_lds_dwordx4 v136, s[34:35]
	s_mov_b32 m0, s47
	s_nop 0
	global_load_lds_dwordx4 v132, s[34:35]
	s_waitcnt vmcnt(8)
	s_waitcnt lgkmcnt(0)
	s_barrier
	s_setprio 1
	v_mfma_f32_16x16x32_bf16 v[62:65], v[158:161], v[190:193], v[62:65]
	v_mfma_f32_16x16x32_bf16 v[58:61], v[166:169], v[190:193], v[58:61]
	v_mfma_f32_16x16x32_bf16 v[50:53], v[158:161], v[206:209], v[50:53]
	v_mfma_f32_16x16x32_bf16 v[42:45], v[166:169], v[206:209], v[42:45]
	v_mfma_f32_16x16x32_bf16 v[34:37], v[158:161], v[214:217], v[34:37]
	v_mfma_f32_16x16x32_bf16 v[26:29], v[166:169], v[214:217], v[26:29]
	v_mfma_f32_16x16x32_bf16 v[18:21], v[158:161], v[222:225], v[18:21]
	v_mfma_f32_16x16x32_bf16 v[10:13], v[166:169], v[222:225], v[10:13]
	v_mfma_f32_16x16x32_bf16 v[62:65], v[162:165], v[194:197], v[62:65]
	v_mfma_f32_16x16x32_bf16 v[58:61], v[170:173], v[194:197], v[58:61]
	v_mfma_f32_16x16x32_bf16 v[50:53], v[162:165], v[210:213], v[50:53]
	v_mfma_f32_16x16x32_bf16 v[42:45], v[170:173], v[210:213], v[42:45]
	v_mfma_f32_16x16x32_bf16 v[34:37], v[162:165], v[218:221], v[34:37]
	v_mfma_f32_16x16x32_bf16 v[26:29], v[170:173], v[218:221], v[26:29]
	v_mfma_f32_16x16x32_bf16 v[18:21], v[162:165], v[226:229], v[18:21]
	v_mfma_f32_16x16x32_bf16 v[10:13], v[170:173], v[226:229], v[10:13]
	v_mfma_f32_16x16x32_bf16 v[54:57], v[174:177], v[190:193], v[54:57]
	v_mfma_f32_16x16x32_bf16 v[46:49], v[182:185], v[190:193], v[46:49]
	v_mfma_f32_16x16x32_bf16 v[38:41], v[174:177], v[206:209], v[38:41]
	v_mfma_f32_16x16x32_bf16 v[30:33], v[182:185], v[206:209], v[30:33]
	v_mfma_f32_16x16x32_bf16 v[22:25], v[174:177], v[214:217], v[22:25]
	v_mfma_f32_16x16x32_bf16 v[14:17], v[182:185], v[214:217], v[14:17]
	v_mfma_f32_16x16x32_bf16 v[6:9], v[174:177], v[222:225], v[6:9]
	v_mfma_f32_16x16x32_bf16 v[2:5], v[182:185], v[222:225], v[2:5]
	v_mfma_f32_16x16x32_bf16 v[54:57], v[178:181], v[194:197], v[54:57]
	v_mfma_f32_16x16x32_bf16 v[46:49], v[186:189], v[194:197], v[46:49]
	v_mfma_f32_16x16x32_bf16 v[38:41], v[178:181], v[210:213], v[38:41]
	v_mfma_f32_16x16x32_bf16 v[30:33], v[186:189], v[210:213], v[30:33]
	v_mfma_f32_16x16x32_bf16 v[22:25], v[178:181], v[218:221], v[22:25]
	v_mfma_f32_16x16x32_bf16 v[14:17], v[186:189], v[218:221], v[14:17]
	v_mfma_f32_16x16x32_bf16 v[6:9], v[178:181], v[226:229], v[6:9]
	v_mfma_f32_16x16x32_bf16 v[2:5], v[186:189], v[226:229], v[2:5]
	s_setprio 0
	s_barrier
; #define PG8_STAGE(bufoff, gbase, voff) do { _Pragma("unroll") for (int _i = 0; _i < 2; ++_i) \
;         __builtin_amdgcn_global_load_lds((const unsigned*)((const char*)(gbase) + (voff)[_i]), (PG8_LAS unsigned*)(lds + (bufoff) + ldsw + _i * 8192), 16, 0, 0); } while (0)
; #define PG8_LDA(dst, b, h) do { _Pragma("unroll") for (int m = 0; m < 4; ++m) _Pragma("unroll") for (int k = 0; k < 2; ++k) dst[m][k] = *(const PG8_LAS bf16x8*)(lds + PG8_SA(b, h) + aoff + m * 2048 + k * 1024); } while (0)
; #define PG8_LDB(dst, b, h) do { _Pragma("unroll") for (int n = 0; n < 2; ++n) _Pragma("unroll") for (int k = 0; k < 2; ++k) dst[n][k] = *(const PG8_LAS bf16x8*)(lds + PG8_SB(b, h) + boff + n * 2048 + k * 1024); } while (0)
; #define PG8_MMA(ai, bj, At, Bt) do { __builtin_amdgcn_s_setprio(1); _Pragma("unroll") for (int m = 0; m < 4; ++m) _Pragma("unroll") for (int n = 0; n < 2; ++n) _Pragma("unroll") for (int k = 0; k < 2; ++k) \
;         acc[ai][bj][m][n] = __builtin_amdgcn_mfma_f32_16x16x32_bf16(Bt[n][k], At[m][k], acc[ai][bj][m][n], 0, 0, 0); __builtin_amdgcn_s_setprio(0); } while (0)
; #define PG8_WAIT_V(n) asm volatile("s_waitcnt vmcnt(" #n ")" ::: "memory")
; #define PG8_WAIT_L(n) asm volatile("s_waitcnt lgkmcnt(" #n ")" ::: "memory")
; #define PG8_BAR __builtin_amdgcn_s_barrier()
; #define PG8_SCHED __builtin_amdgcn_sched_barrier(0)
; template <class Epi, class Sched, bool ALIGN_EPI = false, bool SP2 = false>
; __device__ __forceinline__ void gemm_phase(PG8_LAS unsigned char* lds, const Gemm g, const Sched& S, const Epi& E) {
;     ...
;             PG8_LDB(B0, 1, 0); PG8_LDB(B1, 1, 1); PG8_SCHED; PG8_LDA(At, 1, 0); PG8_STAGE(PG8_SA(0, 1), a2 + hstep, voffA);
;             PG8_WAIT_V(8); PG8_WAIT_L(0); PG8_BAR; PG8_MMA(0, 0, At, B0); PG8_MMA(0, 1, At, B1); PG8_BAR; PG8_SCHED;
;             PG8_LDA(At, 1, 1); PG8_STAGE(PG8_SB(1, 0), b3, voffB); PG8_STAGE(PG8_SB(1, 1), b3 + hstep, voffB); PG8_STAGE(PG8_SA(1, 0), a3, voffA);
;             PG8_WAIT_V(8); PG8_WAIT_L(0); PG8_BAR; PG8_MMA(1, 0, At, B0); PG8_MMA(1, 1, At, B1); PG8_BAR; PG8_SCHED;
	s_add_i32 s20, 0, 0x18000
	v_add_u32_e32 v0, s20, v154
	s_add_i32 s21, 0, 0x1c000
	ds_read_b128 v[158:161], v0
	ds_read_b128 v[162:165], v0 offset:1024
	ds_read_b128 v[166:169], v0 offset:2048
	ds_read_b128 v[170:173], v0 offset:3072
	v_add_u32_e32 v0, s21, v154
	ds_read_b128 v[174:177], v0
	ds_read_b128 v[178:181], v0 offset:1024
	ds_read_b128 v[182:185], v0 offset:2048
	ds_read_b128 v[186:189], v0 offset:3072
	s_add_u32 vcc_lo, s34, 0x40000
	s_addc_u32 vcc_hi, s35, 0
	s_mov_b32 m0, s52
	ds_read_b128 v[190:193], v156 offset:32768
	ds_read_b128 v[194:197], v156 offset:33792
	ds_read_b128 v[206:209], v156 offset:34816
	ds_read_b128 v[210:213], v156 offset:35840
	ds_read_b128 v[214:217], v156 offset:36864
	ds_read_b128 v[218:221], v156 offset:37888
	ds_read_b128 v[222:225], v156 offset:38912
	ds_read_b128 v[226:229], v156 offset:39936
	global_load_lds_dwordx4 v136, vcc
	s_mov_b32 m0, s53
	s_nop 0
	global_load_lds_dwordx4 v132, vcc
	s_waitcnt vmcnt(8)
	s_waitcnt lgkmcnt(0)
	s_barrier
	s_setprio 1
	v_mfma_f32_16x16x32_bf16 v[126:129], v[158:161], v[190:193], v[126:129]
	v_mfma_f32_16x16x32_bf16 v[122:125], v[166:169], v[190:193], v[122:125]
	v_mfma_f32_16x16x32_bf16 v[114:117], v[158:161], v[206:209], v[114:117]
	v_mfma_f32_16x16x32_bf16 v[106:109], v[166:169], v[206:209], v[106:109]
	v_mfma_f32_16x16x32_bf16 v[98:101], v[158:161], v[214:217], v[98:101]
	v_mfma_f32_16x16x32_bf16 v[90:93], v[166:169], v[214:217], v[90:93]
	v_mfma_f32_16x16x32_bf16 v[82:85], v[158:161], v[222:225], v[82:85]
	v_mfma_f32_16x16x32_bf16 v[74:77], v[166:169], v[222:225], v[74:77]
	v_mfma_f32_16x16x32_bf16 v[126:129], v[162:165], v[194:197], v[126:129]
	v_mfma_f32_16x16x32_bf16 v[122:125], v[170:173], v[194:197], v[122:125]
	v_mfma_f32_16x16x32_bf16 v[114:117], v[162:165], v[210:213], v[114:117]
	v_mfma_f32_16x16x32_bf16 v[106:109], v[170:173], v[210:213], v[106:109]
	v_mfma_f32_16x16x32_bf16 v[98:101], v[162:165], v[218:221], v[98:101]
	v_mfma_f32_16x16x32_bf16 v[90:93], v[170:173], v[218:221], v[90:93]
	v_mfma_f32_16x16x32_bf16 v[82:85], v[162:165], v[226:229], v[82:85]
	v_mfma_f32_16x16x32_bf16 v[74:77], v[170:173], v[226:229], v[74:77]
	v_mfma_f32_16x16x32_bf16 v[118:121], v[174:177], v[190:193], v[118:121]
	v_mfma_f32_16x16x32_bf16 v[110:113], v[182:185], v[190:193], v[110:113]
	v_mfma_f32_16x16x32_bf16 v[102:105], v[174:177], v[206:209], v[102:105]
	v_mfma_f32_16x16x32_bf16 v[94:97], v[182:185], v[206:209], v[94:97]
	v_mfma_f32_16x16x32_bf16 v[86:89], v[174:177], v[214:217], v[86:89]
	v_mfma_f32_16x16x32_bf16 v[78:81], v[182:185], v[214:217], v[78:81]
	v_mfma_f32_16x16x32_bf16 v[70:73], v[174:177], v[222:225], v[70:73]
	v_mfma_f32_16x16x32_bf16 v[66:69], v[182:185], v[222:225], v[66:69]
	v_mfma_f32_16x16x32_bf16 v[118:121], v[178:181], v[194:197], v[118:121]
	v_mfma_f32_16x16x32_bf16 v[110:113], v[186:189], v[194:197], v[110:113]
	v_mfma_f32_16x16x32_bf16 v[102:105], v[178:181], v[210:213], v[102:105]
	v_mfma_f32_16x16x32_bf16 v[94:97], v[186:189], v[210:213], v[94:97]
	v_mfma_f32_16x16x32_bf16 v[86:89], v[178:181], v[218:221], v[86:89]
	v_mfma_f32_16x16x32_bf16 v[78:81], v[186:189], v[218:221], v[78:81]
	v_mfma_f32_16x16x32_bf16 v[70:73], v[178:181], v[226:229], v[70:73]
	v_mfma_f32_16x16x32_bf16 v[66:69], v[186:189], v[226:229], v[66:69]
	s_setprio 0
	s_barrier
	s_add_i32 s20, s20, s29
	s_add_i32 m0, s20, 0xffffff80
	ds_read_b128 v[190:193], v156 offset:49152
	ds_read_b128 v[194:197], v156 offset:50176
	ds_read_b128 v[206:209], v156 offset:51200
	ds_read_b128 v[210:213], v156 offset:52224
	ds_read_b128 v[214:217], v156 offset:53248
	ds_read_b128 v[218:221], v156 offset:54272
	ds_read_b128 v[222:225], v156 offset:55296
	ds_read_b128 v[226:229], v156 offset:56320
	global_load_lds_dwordx4 v134, s[30:31] offset:128
	s_add_i32 m0, s20, 0x1f80
	s_add_i32 s20, s21, s29
	global_load_lds_dwordx4 v130, s[30:31] offset:128
	s_add_u32 s30, s30, 0x40080
	s_addc_u32 s31, s31, 0
	s_mov_b32 m0, s20
	s_nop 0
	global_load_lds_dwordx4 v134, s[30:31]
	s_add_i32 m0, s20, 0x2000
	s_nop 0
	global_load_lds_dwordx4 v130, s[30:31]
	s_add_i32 m0, s55, 0xffffff80
	s_nop 0
	global_load_lds_dwordx4 v136, s[34:35] offset:128
	s_add_i32 m0, s57, 0xffffff80
	s_nop 0
	global_load_lds_dwordx4 v132, s[34:35] offset:128
	s_waitcnt vmcnt(8)
	s_waitcnt lgkmcnt(0)
	s_barrier
	s_setprio 1
	v_mfma_f32_16x16x32_bf16 v[62:65], v[158:161], v[190:193], v[62:65]
	v_mfma_f32_16x16x32_bf16 v[58:61], v[166:169], v[190:193], v[58:61]
	v_mfma_f32_16x16x32_bf16 v[50:53], v[158:161], v[206:209], v[50:53]
	v_mfma_f32_16x16x32_bf16 v[42:45], v[166:169], v[206:209], v[42:45]
	v_mfma_f32_16x16x32_bf16 v[34:37], v[158:161], v[214:217], v[34:37]
	v_mfma_f32_16x16x32_bf16 v[26:29], v[166:169], v[214:217], v[26:29]
	v_mfma_f32_16x16x32_bf16 v[18:21], v[158:161], v[222:225], v[18:21]
	v_mfma_f32_16x16x32_bf16 v[10:13], v[166:169], v[222:225], v[10:13]
	v_mfma_f32_16x16x32_bf16 v[62:65], v[162:165], v[194:197], v[62:65]
	v_mfma_f32_16x16x32_bf16 v[58:61], v[170:173], v[194:197], v[58:61]
	v_mfma_f32_16x16x32_bf16 v[50:53], v[162:165], v[210:213], v[50:53]
	v_mfma_f32_16x16x32_bf16 v[42:45], v[170:173], v[210:213], v[42:45]
	v_mfma_f32_16x16x32_bf16 v[34:37], v[162:165], v[218:221], v[34:37]
	v_mfma_f32_16x16x32_bf16 v[26:29], v[170:173], v[218:221], v[26:29]
	v_mfma_f32_16x16x32_bf16 v[18:21], v[162:165], v[226:229], v[18:21]
	v_mfma_f32_16x16x32_bf16 v[10:13], v[170:173], v[226:229], v[10:13]
	v_mfma_f32_16x16x32_bf16 v[54:57], v[174:177], v[190:193], v[54:57]
	v_mfma_f32_16x16x32_bf16 v[46:49], v[182:185], v[190:193], v[46:49]
	v_mfma_f32_16x16x32_bf16 v[38:41], v[174:177], v[206:209], v[38:41]
	v_mfma_f32_16x16x32_bf16 v[30:33], v[182:185], v[206:209], v[30:33]
	v_mfma_f32_16x16x32_bf16 v[22:25], v[174:177], v[214:217], v[22:25]
	v_mfma_f32_16x16x32_bf16 v[14:17], v[182:185], v[214:217], v[14:17]
	v_mfma_f32_16x16x32_bf16 v[6:9], v[174:177], v[222:225], v[6:9]
	v_mfma_f32_16x16x32_bf16 v[2:5], v[182:185], v[222:225], v[2:5]
	v_mfma_f32_16x16x32_bf16 v[54:57], v[178:181], v[194:197], v[54:57]
	v_mfma_f32_16x16x32_bf16 v[46:49], v[186:189], v[194:197], v[46:49]
	v_mfma_f32_16x16x32_bf16 v[38:41], v[178:181], v[210:213], v[38:41]
	v_mfma_f32_16x16x32_bf16 v[30:33], v[186:189], v[210:213], v[30:33]
	v_mfma_f32_16x16x32_bf16 v[22:25], v[178:181], v[218:221], v[22:25]
	v_mfma_f32_16x16x32_bf16 v[14:17], v[186:189], v[218:221], v[14:17]
	v_mfma_f32_16x16x32_bf16 v[6:9], v[178:181], v[226:229], v[6:9]
	v_mfma_f32_16x16x32_bf16 v[2:5], v[186:189], v[226:229], v[2:5]
	s_setprio 0
	s_barrier
	s_add_i32 s40, s40, 2
	s_add_u32 s8, s8, 0x100
	s_addc_u32 s9, s9, 0
	s_add_u32 s38, s38, 0x100
	s_addc_u32 s39, s39, 0
	s_cmp_gt_u32 s40, 13
	s_cbranch_scc0 .LBB0_114
	s_and_b64 vcc, exec, s[6:7]
	s_cbranch_vccz .LBB0_117
	s_barrier

; #define PG8_STAGE(bufoff, gbase, voff) do { _Pragma("unroll") for (int _i = 0; _i < 2; ++_i) \
;         __builtin_amdgcn_global_load_lds((const unsigned*)((const char*)(gbase) + (voff)[_i]), (PG8_LAS unsigned*)(lds + (bufoff) + ldsw + _i * 8192), 16, 0, 0); } while (0)
; #define PG8_LDA(dst, b, h) do { _Pragma("unroll") for (int m = 0; m < 4; ++m) _Pragma("unroll") for (int k = 0; k < 2; ++k) dst[m][k] = *(const PG8_LAS bf16x8*)(lds + PG8_SA(b, h) + aoff + m * 2048 + k * 1024); } while (0)
; #define PG8_LDB(dst, b, h) do { _Pragma("unroll") for (int n = 0; n < 2; ++n) _Pragma("unroll") for (int k = 0; k < 2; ++k) dst[n][k] = *(const PG8_LAS bf16x8*)(lds + PG8_SB(b, h) + boff + n * 2048 + k * 1024); } while (0)
; #define PG8_MMA(ai, bj, At, Bt) do { __builtin_amdgcn_s_setprio(1); _Pragma("unroll") for (int m = 0; m < 4; ++m) _Pragma("unroll") for (int n = 0; n < 2; ++n) _Pragma("unroll") for (int k = 0; k < 2; ++k) \
;         acc[ai][bj][m][n] = __builtin_amdgcn_mfma_f32_16x16x32_bf16(Bt[n][k], At[m][k], acc[ai][bj][m][n], 0, 0, 0); __builtin_amdgcn_s_setprio(0); } while (0)
; #define PG8_WAIT_V(n) asm volatile("s_waitcnt vmcnt(" #n ")" ::: "memory")
; #define PG8_WAIT_L(n) asm volatile("s_waitcnt lgkmcnt(" #n ")" ::: "memory")
; #define PG8_BAR __builtin_amdgcn_s_barrier()
; #define PG8_SCHED __builtin_amdgcn_sched_barrier(0)
; template <class Epi, class Sched, bool ALIGN_EPI = false, bool SP2 = false>
; __device__ __forceinline__ void gemm_phase(PG8_LAS unsigned char* lds, const Gemm g, const Sched& S, const Epi& E) {
;     ...
;             PG8_LDB(B0, 0, 0); PG8_LDB(B1, 0, 1); PG8_SCHED; PG8_LDA(At, 0, 0); PG8_STAGE(PG8_SA(1, 1), a1 + hstep, voffA);
;             PG8_WAIT_V(8); PG8_WAIT_L(0); PG8_BAR; PG8_MMA(0, 0, At, B0); PG8_MMA(0, 1, At, B1); PG8_BAR; PG8_SCHED;
;             PG8_LDA(At, 0, 1); PG8_STAGE(PG8_SB(0, 0), b2, voffB); PG8_STAGE(PG8_SB(0, 1), b2 + hstep, voffB); PG8_STAGE(PG8_SA(0, 0), a2, voffA);
;             PG8_WAIT_V(8); PG8_WAIT_L(0); PG8_BAR; PG8_MMA(1, 0, At, B0); PG8_MMA(1, 1, At, B1); PG8_BAR; PG8_SCHED;
.LBB0_144:
	s_add_u32 s20, s8, 0xfffc0080
	s_addc_u32 s21, s9, -1
	s_add_i32 s80, 0, 0x10000
	s_cmp_eq_u32 s73, 12
	s_cselect_b32 s39, s17, s21
	s_cselect_b32 s38, s40, s20
	v_add_u32_e32 v149, s80, v147
	s_cselect_b32 s35, s13, s72
	s_cselect_b32 s34, s41, s46
	s_add_i32 s20, 0, 0x14000
	ds_read_b128 v[142:145], v149
	ds_read_b128 v[150:153], v149 offset:1024
	ds_read_b128 v[154:157], v149 offset:2048
	ds_read_b128 v[158:161], v149 offset:3072
	v_add_u32_e32 v149, s20, v147
	ds_read_b128 v[162:165], v149
	ds_read_b128 v[166:169], v149 offset:1024
	ds_read_b128 v[170:173], v149 offset:2048
	ds_read_b128 v[174:177], v149 offset:3072
	s_add_i32 m0, s28, 0xc000
	ds_read_b128 v[178:181], v148
	ds_read_b128 v[182:185], v148 offset:1024
	ds_read_b128 v[186:189], v148 offset:2048
	ds_read_b128 v[190:193], v148 offset:3072
	ds_read_b128 v[194:197], v148 offset:4096
	ds_read_b128 v[206:209], v148 offset:5120
	ds_read_b128 v[210:213], v148 offset:6144
	ds_read_b128 v[214:217], v148 offset:7168
	global_load_lds_dwordx4 v138, s[8:9]
	s_add_i32 m0, s28, 0xe000
	s_nop 0
	global_load_lds_dwordx4 v140, s[8:9]
	s_waitcnt vmcnt(8)
	s_waitcnt lgkmcnt(0)
	s_barrier
	s_setprio 1
	v_mfma_f32_16x16x32_bf16 v[126:129], v[142:145], v[178:181], v[126:129]
	v_mfma_f32_16x16x32_bf16 v[122:125], v[154:157], v[178:181], v[122:125]
	v_mfma_f32_16x16x32_bf16 v[110:113], v[142:145], v[186:189], v[110:113]
	v_mfma_f32_16x16x32_bf16 v[106:109], v[154:157], v[186:189], v[106:109]
	v_mfma_f32_16x16x32_bf16 v[94:97], v[142:145], v[194:197], v[94:97]
	v_mfma_f32_16x16x32_bf16 v[90:93], v[154:157], v[194:197], v[90:93]
	v_mfma_f32_16x16x32_bf16 v[78:81], v[142:145], v[210:213], v[78:81]
	v_mfma_f32_16x16x32_bf16 v[74:77], v[154:157], v[210:213], v[74:77]
	v_mfma_f32_16x16x32_bf16 v[126:129], v[150:153], v[182:185], v[126:129]
	v_mfma_f32_16x16x32_bf16 v[122:125], v[158:161], v[182:185], v[122:125]
	v_mfma_f32_16x16x32_bf16 v[110:113], v[150:153], v[190:193], v[110:113]
	v_mfma_f32_16x16x32_bf16 v[106:109], v[158:161], v[190:193], v[106:109]
	v_mfma_f32_16x16x32_bf16 v[94:97], v[150:153], v[206:209], v[94:97]
	v_mfma_f32_16x16x32_bf16 v[90:93], v[158:161], v[206:209], v[90:93]
	v_mfma_f32_16x16x32_bf16 v[78:81], v[150:153], v[214:217], v[78:81]
	v_mfma_f32_16x16x32_bf16 v[74:77], v[158:161], v[214:217], v[74:77]
	v_mfma_f32_16x16x32_bf16 v[118:121], v[162:165], v[178:181], v[118:121]
	v_mfma_f32_16x16x32_bf16 v[114:117], v[170:173], v[178:181], v[114:117]
	v_mfma_f32_16x16x32_bf16 v[102:105], v[162:165], v[186:189], v[102:105]
	v_mfma_f32_16x16x32_bf16 v[98:101], v[170:173], v[186:189], v[98:101]
	v_mfma_f32_16x16x32_bf16 v[86:89], v[162:165], v[194:197], v[86:89]
	v_mfma_f32_16x16x32_bf16 v[82:85], v[170:173], v[194:197], v[82:85]
	v_mfma_f32_16x16x32_bf16 v[70:73], v[162:165], v[210:213], v[70:73]
	v_mfma_f32_16x16x32_bf16 v[66:69], v[170:173], v[210:213], v[66:69]
	v_mfma_f32_16x16x32_bf16 v[118:121], v[166:169], v[182:185], v[118:121]
	v_mfma_f32_16x16x32_bf16 v[114:117], v[174:177], v[182:185], v[114:117]
	v_mfma_f32_16x16x32_bf16 v[102:105], v[166:169], v[190:193], v[102:105]
	v_mfma_f32_16x16x32_bf16 v[98:101], v[174:177], v[190:193], v[98:101]
	v_mfma_f32_16x16x32_bf16 v[86:89], v[166:169], v[206:209], v[86:89]
	v_mfma_f32_16x16x32_bf16 v[82:85], v[174:177], v[206:209], v[82:85]
	v_mfma_f32_16x16x32_bf16 v[70:73], v[166:169], v[214:217], v[70:73]
	v_mfma_f32_16x16x32_bf16 v[66:69], v[174:177], v[214:217], v[66:69]
	s_setprio 0
	s_barrier
	s_add_i32 s21, s80, s47
	s_mov_b32 m0, s21
	ds_read_b128 v[178:181], v148 offset:16384
	ds_read_b128 v[182:185], v148 offset:17408
	ds_read_b128 v[186:189], v148 offset:18432
	ds_read_b128 v[190:193], v148 offset:19456
	ds_read_b128 v[194:197], v148 offset:20480
	ds_read_b128 v[206:209], v148 offset:21504
	ds_read_b128 v[210:213], v148 offset:22528
	ds_read_b128 v[214:217], v148 offset:23552
	global_load_lds_dwordx4 v0, s[34:35]
	s_add_i32 m0, s21, 0x2000
	s_add_u32 s82, s34, 0x40000
	s_addc_u32 s83, s35, 0
	s_add_i32 s20, s20, s47
	global_load_lds_dwordx4 v130, s[34:35]
	s_mov_b32 m0, s20
	s_nop 0
	global_load_lds_dwordx4 v0, s[82:83]
	s_add_i32 m0, s20, 0x2000
	s_nop 0
	global_load_lds_dwordx4 v130, s[82:83]
	s_mov_b32 m0, s28
	s_nop 0
	global_load_lds_dwordx4 v134, s[38:39]
	s_mov_b32 m0, s29
	s_nop 0
	global_load_lds_dwordx4 v132, s[38:39]
	s_waitcnt vmcnt(8)
	s_waitcnt lgkmcnt(0)
	s_barrier
	s_setprio 1
	v_mfma_f32_16x16x32_bf16 v[62:65], v[142:145], v[178:181], v[62:65]
	v_mfma_f32_16x16x32_bf16 v[58:61], v[154:157], v[178:181], v[58:61]
	v_mfma_f32_16x16x32_bf16 v[46:49], v[142:145], v[186:189], v[46:49]
	v_mfma_f32_16x16x32_bf16 v[42:45], v[154:157], v[186:189], v[42:45]
	v_mfma_f32_16x16x32_bf16 v[30:33], v[142:145], v[194:197], v[30:33]
	v_mfma_f32_16x16x32_bf16 v[26:29], v[154:157], v[194:197], v[26:29]
	v_mfma_f32_16x16x32_bf16 v[14:17], v[142:145], v[210:213], v[14:17]
	v_mfma_f32_16x16x32_bf16 v[10:13], v[154:157], v[210:213], v[10:13]
	v_mfma_f32_16x16x32_bf16 v[62:65], v[150:153], v[182:185], v[62:65]
	v_mfma_f32_16x16x32_bf16 v[58:61], v[158:161], v[182:185], v[58:61]
	v_mfma_f32_16x16x32_bf16 v[46:49], v[150:153], v[190:193], v[46:49]
	v_mfma_f32_16x16x32_bf16 v[42:45], v[158:161], v[190:193], v[42:45]
	v_mfma_f32_16x16x32_bf16 v[30:33], v[150:153], v[206:209], v[30:33]
	v_mfma_f32_16x16x32_bf16 v[26:29], v[158:161], v[206:209], v[26:29]
	v_mfma_f32_16x16x32_bf16 v[14:17], v[150:153], v[214:217], v[14:17]
	v_mfma_f32_16x16x32_bf16 v[10:13], v[158:161], v[214:217], v[10:13]
	v_mfma_f32_16x16x32_bf16 v[54:57], v[162:165], v[178:181], v[54:57]
	v_mfma_f32_16x16x32_bf16 v[50:53], v[170:173], v[178:181], v[50:53]
	v_mfma_f32_16x16x32_bf16 v[38:41], v[162:165], v[186:189], v[38:41]
	v_mfma_f32_16x16x32_bf16 v[34:37], v[170:173], v[186:189], v[34:37]
	v_mfma_f32_16x16x32_bf16 v[22:25], v[162:165], v[194:197], v[22:25]
	v_mfma_f32_16x16x32_bf16 v[18:21], v[170:173], v[194:197], v[18:21]
	v_mfma_f32_16x16x32_bf16 v[6:9], v[162:165], v[210:213], v[6:9]
	v_mfma_f32_16x16x32_bf16 v[2:5], v[170:173], v[210:213], v[2:5]
	v_mfma_f32_16x16x32_bf16 v[54:57], v[166:169], v[182:185], v[54:57]
	v_mfma_f32_16x16x32_bf16 v[50:53], v[174:177], v[182:185], v[50:53]
	v_mfma_f32_16x16x32_bf16 v[38:41], v[166:169], v[190:193], v[38:41]
	v_mfma_f32_16x16x32_bf16 v[34:37], v[174:177], v[190:193], v[34:37]
	v_mfma_f32_16x16x32_bf16 v[22:25], v[166:169], v[206:209], v[22:25]
	v_mfma_f32_16x16x32_bf16 v[18:21], v[174:177], v[206:209], v[18:21]
	v_mfma_f32_16x16x32_bf16 v[6:9], v[166:169], v[214:217], v[6:9]
	v_mfma_f32_16x16x32_bf16 v[2:5], v[174:177], v[214:217], v[2:5]
	s_setprio 0
	s_barrier
; #define PG8_STAGE(bufoff, gbase, voff) do { _Pragma("unroll") for (int _i = 0; _i < 2; ++_i) \
;         __builtin_amdgcn_global_load_lds((const unsigned*)((const char*)(gbase) + (voff)[_i]), (PG8_LAS unsigned*)(lds + (bufoff) + ldsw + _i * 8192), 16, 0, 0); } while (0)
; #define PG8_LDA(dst, b, h) do { _Pragma("unroll") for (int m = 0; m < 4; ++m) _Pragma("unroll") for (int k = 0; k < 2; ++k) dst[m][k] = *(const PG8_LAS bf16x8*)(lds + PG8_SA(b, h) + aoff + m * 2048 + k * 1024); } while (0)
; #define PG8_LDB(dst, b, h) do { _Pragma("unroll") for (int n = 0; n < 2; ++n) _Pragma("unroll") for (int k = 0; k < 2; ++k) dst[n][k] = *(const PG8_LAS bf16x8*)(lds + PG8_SB(b, h) + boff + n * 2048 + k * 1024); } while (0)
; #define PG8_MMA(ai, bj, At, Bt) do { __builtin_amdgcn_s_setprio(1); _Pragma("unroll") for (int m = 0; m < 4; ++m) _Pragma("unroll") for (int n = 0; n < 2; ++n) _Pragma("unroll") for (int k = 0; k < 2; ++k) \
;         acc[ai][bj][m][n] = __builtin_amdgcn_mfma_f32_16x16x32_bf16(Bt[n][k], At[m][k], acc[ai][bj][m][n], 0, 0, 0); __builtin_amdgcn_s_setprio(0); } while (0)
; #define PG8_WAIT_V(n) asm volatile("s_waitcnt vmcnt(" #n ")" ::: "memory")
; #define PG8_WAIT_L(n) asm volatile("s_waitcnt lgkmcnt(" #n ")" ::: "memory")
; #define PG8_BAR __builtin_amdgcn_s_barrier()
; #define PG8_SCHED __builtin_amdgcn_sched_barrier(0)
; template <class Epi, class Sched, bool ALIGN_EPI = false, bool SP2 = false>
; __device__ __forceinline__ void gemm_phase(PG8_LAS unsigned char* lds, const Gemm g, const Sched& S, const Epi& E) {
;     ...
;             PG8_LDB(B0, 1, 0); PG8_LDB(B1, 1, 1); PG8_SCHED; PG8_LDA(At, 1, 0); PG8_STAGE(PG8_SA(0, 1), a2 + hstep, voffA);
;             PG8_WAIT_V(8); PG8_WAIT_L(0); PG8_BAR; PG8_MMA(0, 0, At, B0); PG8_MMA(0, 1, At, B1); PG8_BAR; PG8_SCHED;
;             PG8_LDA(At, 1, 1); PG8_STAGE(PG8_SB(1, 0), b3, voffB); PG8_STAGE(PG8_SB(1, 1), b3 + hstep, voffB); PG8_STAGE(PG8_SA(1, 0), a3, voffA);
;             PG8_WAIT_V(8); PG8_WAIT_L(0); PG8_BAR; PG8_MMA(1, 0, At, B0); PG8_MMA(1, 1, At, B1); PG8_BAR; PG8_SCHED;
	s_add_i32 s20, 0, 0x18000
	v_add_u32_e32 v149, s20, v147
	s_add_i32 s21, 0, 0x1c000
	ds_read_b128 v[142:145], v149
	ds_read_b128 v[150:153], v149 offset:1024
	ds_read_b128 v[154:157], v149 offset:2048
	ds_read_b128 v[158:161], v149 offset:3072
	v_add_u32_e32 v149, s21, v147
	ds_read_b128 v[162:165], v149
	ds_read_b128 v[166:169], v149 offset:1024
	ds_read_b128 v[170:173], v149 offset:2048
	ds_read_b128 v[174:177], v149 offset:3072
	s_add_u32 vcc_lo, s38, 0x40000
	s_addc_u32 vcc_hi, s39, 0
	s_mov_b32 m0, s52
	ds_read_b128 v[178:181], v148 offset:32768
	ds_read_b128 v[182:185], v148 offset:33792
	ds_read_b128 v[186:189], v148 offset:34816
	ds_read_b128 v[190:193], v148 offset:35840
	ds_read_b128 v[194:197], v148 offset:36864
	ds_read_b128 v[206:209], v148 offset:37888
	ds_read_b128 v[210:213], v148 offset:38912
	ds_read_b128 v[214:217], v148 offset:39936
	global_load_lds_dwordx4 v134, vcc
	s_mov_b32 m0, s53
	s_nop 0
	global_load_lds_dwordx4 v132, vcc
	s_waitcnt vmcnt(8)
	s_waitcnt lgkmcnt(0)
	s_barrier
	s_setprio 1
	v_mfma_f32_16x16x32_bf16 v[126:129], v[142:145], v[178:181], v[126:129]
	v_mfma_f32_16x16x32_bf16 v[122:125], v[154:157], v[178:181], v[122:125]
	v_mfma_f32_16x16x32_bf16 v[110:113], v[142:145], v[186:189], v[110:113]
	v_mfma_f32_16x16x32_bf16 v[106:109], v[154:157], v[186:189], v[106:109]
	v_mfma_f32_16x16x32_bf16 v[94:97], v[142:145], v[194:197], v[94:97]
	v_mfma_f32_16x16x32_bf16 v[90:93], v[154:157], v[194:197], v[90:93]
	v_mfma_f32_16x16x32_bf16 v[78:81], v[142:145], v[210:213], v[78:81]
	v_mfma_f32_16x16x32_bf16 v[74:77], v[154:157], v[210:213], v[74:77]
	v_mfma_f32_16x16x32_bf16 v[126:129], v[150:153], v[182:185], v[126:129]
	v_mfma_f32_16x16x32_bf16 v[122:125], v[158:161], v[182:185], v[122:125]
	v_mfma_f32_16x16x32_bf16 v[110:113], v[150:153], v[190:193], v[110:113]
	v_mfma_f32_16x16x32_bf16 v[106:109], v[158:161], v[190:193], v[106:109]
	v_mfma_f32_16x16x32_bf16 v[94:97], v[150:153], v[206:209], v[94:97]
	v_mfma_f32_16x16x32_bf16 v[90:93], v[158:161], v[206:209], v[90:93]
	v_mfma_f32_16x16x32_bf16 v[78:81], v[150:153], v[214:217], v[78:81]
	v_mfma_f32_16x16x32_bf16 v[74:77], v[158:161], v[214:217], v[74:77]
	v_mfma_f32_16x16x32_bf16 v[118:121], v[162:165], v[178:181], v[118:121]
	v_mfma_f32_16x16x32_bf16 v[114:117], v[170:173], v[178:181], v[114:117]
	v_mfma_f32_16x16x32_bf16 v[102:105], v[162:165], v[186:189], v[102:105]
	v_mfma_f32_16x16x32_bf16 v[98:101], v[170:173], v[186:189], v[98:101]
	v_mfma_f32_16x16x32_bf16 v[86:89], v[162:165], v[194:197], v[86:89]
	v_mfma_f32_16x16x32_bf16 v[82:85], v[170:173], v[194:197], v[82:85]
	v_mfma_f32_16x16x32_bf16 v[70:73], v[162:165], v[210:213], v[70:73]
	v_mfma_f32_16x16x32_bf16 v[66:69], v[170:173], v[210:213], v[66:69]
	v_mfma_f32_16x16x32_bf16 v[118:121], v[166:169], v[182:185], v[118:121]
	v_mfma_f32_16x16x32_bf16 v[114:117], v[174:177], v[182:185], v[114:117]
	v_mfma_f32_16x16x32_bf16 v[102:105], v[166:169], v[190:193], v[102:105]
	v_mfma_f32_16x16x32_bf16 v[98:101], v[174:177], v[190:193], v[98:101]
	v_mfma_f32_16x16x32_bf16 v[86:89], v[166:169], v[206:209], v[86:89]
	v_mfma_f32_16x16x32_bf16 v[82:85], v[174:177], v[206:209], v[82:85]
	v_mfma_f32_16x16x32_bf16 v[70:73], v[166:169], v[214:217], v[70:73]
	v_mfma_f32_16x16x32_bf16 v[66:69], v[174:177], v[214:217], v[66:69]
	s_setprio 0
	s_barrier
	s_add_i32 s20, s20, s47
	s_add_i32 m0, s20, 0xffffff80
	ds_read_b128 v[178:181], v148 offset:49152
	ds_read_b128 v[182:185], v148 offset:50176
	ds_read_b128 v[186:189], v148 offset:51200
	ds_read_b128 v[190:193], v148 offset:52224
	ds_read_b128 v[194:197], v148 offset:53248
	ds_read_b128 v[206:209], v148 offset:54272
	ds_read_b128 v[210:213], v148 offset:55296
	ds_read_b128 v[214:217], v148 offset:56320
	global_load_lds_dwordx4 v0, s[34:35] offset:128
	s_add_i32 m0, s20, 0x1f80
	s_add_i32 s20, s21, s47
	global_load_lds_dwordx4 v130, s[34:35] offset:128
	s_add_u32 s34, s34, 0x40080
	s_addc_u32 s35, s35, 0
	s_mov_b32 m0, s20
	s_nop 0
	global_load_lds_dwordx4 v0, s[34:35]
	s_add_i32 m0, s20, 0x2000
	s_nop 0
	global_load_lds_dwordx4 v130, s[34:35]
	s_add_i32 m0, s55, 0xffffff80
	s_nop 0
	global_load_lds_dwordx4 v134, s[38:39] offset:128
	s_add_i32 m0, s57, 0xffffff80
	s_nop 0
	global_load_lds_dwordx4 v132, s[38:39] offset:128
	s_waitcnt vmcnt(8)
	s_waitcnt lgkmcnt(0)
	s_barrier
	s_setprio 1
	v_mfma_f32_16x16x32_bf16 v[62:65], v[142:145], v[178:181], v[62:65]
	v_mfma_f32_16x16x32_bf16 v[58:61], v[154:157], v[178:181], v[58:61]
	v_mfma_f32_16x16x32_bf16 v[46:49], v[142:145], v[186:189], v[46:49]
	v_mfma_f32_16x16x32_bf16 v[42:45], v[154:157], v[186:189], v[42:45]
	v_mfma_f32_16x16x32_bf16 v[30:33], v[142:145], v[194:197], v[30:33]
	v_mfma_f32_16x16x32_bf16 v[26:29], v[154:157], v[194:197], v[26:29]
	v_mfma_f32_16x16x32_bf16 v[14:17], v[142:145], v[210:213], v[14:17]
	v_mfma_f32_16x16x32_bf16 v[10:13], v[154:157], v[210:213], v[10:13]
	v_mfma_f32_16x16x32_bf16 v[62:65], v[150:153], v[182:185], v[62:65]
	v_mfma_f32_16x16x32_bf16 v[58:61], v[158:161], v[182:185], v[58:61]
	v_mfma_f32_16x16x32_bf16 v[46:49], v[150:153], v[190:193], v[46:49]
	v_mfma_f32_16x16x32_bf16 v[42:45], v[158:161], v[190:193], v[42:45]
	v_mfma_f32_16x16x32_bf16 v[30:33], v[150:153], v[206:209], v[30:33]
	v_mfma_f32_16x16x32_bf16 v[26:29], v[158:161], v[206:209], v[26:29]
	v_mfma_f32_16x16x32_bf16 v[14:17], v[150:153], v[214:217], v[14:17]
	v_mfma_f32_16x16x32_bf16 v[10:13], v[158:161], v[214:217], v[10:13]
	v_mfma_f32_16x16x32_bf16 v[54:57], v[162:165], v[178:181], v[54:57]
	v_mfma_f32_16x16x32_bf16 v[50:53], v[170:173], v[178:181], v[50:53]
	v_mfma_f32_16x16x32_bf16 v[38:41], v[162:165], v[186:189], v[38:41]
	v_mfma_f32_16x16x32_bf16 v[34:37], v[170:173], v[186:189], v[34:37]
	v_mfma_f32_16x16x32_bf16 v[22:25], v[162:165], v[194:197], v[22:25]
	v_mfma_f32_16x16x32_bf16 v[18:21], v[170:173], v[194:197], v[18:21]
	v_mfma_f32_16x16x32_bf16 v[6:9], v[162:165], v[210:213], v[6:9]
	v_mfma_f32_16x16x32_bf16 v[2:5], v[170:173], v[210:213], v[2:5]
	v_mfma_f32_16x16x32_bf16 v[54:57], v[166:169], v[182:185], v[54:57]
	v_mfma_f32_16x16x32_bf16 v[50:53], v[174:177], v[182:185], v[50:53]
	v_mfma_f32_16x16x32_bf16 v[38:41], v[166:169], v[190:193], v[38:41]
	v_mfma_f32_16x16x32_bf16 v[34:37], v[174:177], v[190:193], v[34:37]
	v_mfma_f32_16x16x32_bf16 v[22:25], v[166:169], v[206:209], v[22:25]
	v_mfma_f32_16x16x32_bf16 v[18:21], v[174:177], v[206:209], v[18:21]
	v_mfma_f32_16x16x32_bf16 v[6:9], v[166:169], v[214:217], v[6:9]
	v_mfma_f32_16x16x32_bf16 v[2:5], v[174:177], v[214:217], v[2:5]
	s_setprio 0
	s_barrier
	s_add_i32 s73, s73, 2
	s_add_u32 s8, s8, 0x100
	s_addc_u32 s9, s9, 0
	s_add_u32 s46, s46, 0x100
	s_addc_u32 s72, s72, 0
	s_cmp_gt_u32 s73, 13
	s_cbranch_scc0 .LBB0_144
	s_and_b64 vcc, exec, s[6:7]
	s_cbranch_vccz .LBB0_147
	s_barrier
